# same as previous plus 32 B of s_nop at the P6 phase entry so the P6 K-loop head sits at a 64 B boundary again
# speedup vs baseline: 1.0016x; 1.0016x over previous
.LBB0_522:
	s_nop 0
	s_nop 0
	s_nop 0
	s_nop 0
	s_nop 0
	s_nop 0
	s_nop 0
	s_nop 0
	s_cmp_lt_i32 s80, 7
	s_cselect_b64 s[0:1], -1, 0
	s_cmp_gt_i32 s81, 6
	s_cselect_b64 s[4:5], -1, 0
	s_and_b64 s[0:1], s[0:1], s[4:5]
	s_andn2_b64 vcc, exec, s[0:1]
	s_cbranch_vccnz .LBB0_622
	v_lshrrev_b32_e32 v2, 1, v144
	v_lshrrev_b32_e32 v3, 5, v144
	v_and_b32_e32 v2, 24, v2
	v_and_b32_e32 v3, 4, v3
	v_bfe_u32 v4, v144, 2, 2
	v_lshlrev_b32_e32 v0, 4, v144
	v_and_b32_e32 v1, 32, v144
	v_bfe_u32 v10, v144, 2, 4
	v_or3_b32 v2, v3, v4, v2
	v_lshrrev_b32_e32 v3, 3, v144
	s_movk_i32 s0, 0x70
	v_bitop3_b32 v8, v0, v1, 48 bitop3:0x6c
	v_and_b32_e32 v9, 64, v144
	v_and_or_b32 v4, v3, s0, v10
	s_movk_i32 s0, 0x60
	v_add_u32_e32 v11, 0x2000, v0
	v_or_b32_e32 v1, v8, v9
	v_and_or_b32 v3, v3, s0, v2
	v_lshrrev_b32_e32 v0, 7, v11
	s_movk_i32 s0, 0xf0
	s_add_u32 s30, s62, 0x4000000
	v_lshl_or_b32 v150, v4, 12, v1
	v_and_or_b32 v3, v0, s0, v10
	s_movk_i32 s0, 0xe0
	s_addc_u32 s31, s63, 0
	v_and_or_b32 v0, v0, s0, v2
	s_lshl_b32 s0, s2, 2
	s_and_b32 s0, s0, 28
	s_ashr_i32 s1, s2, 6
	s_add_i32 s0, s0, s1
	s_waitcnt lgkmcnt(0)
	s_bfe_u32 s16, s2, 0x30003
	s_ashr_i32 s1, s0, 31
	s_lshl_b64 s[6:7], s[0:1], 20
	s_lshl_b32 s2, s16, 20
	s_add_u32 s1, s62, s2
	s_addc_u32 s3, s63, 0
	s_add_u32 s4, s1, 0x1200000
	s_addc_u32 s5, s3, 0
	s_add_u32 s8, s1, 0x1280000
	s_addc_u32 s9, s3, 0
	s_add_u32 s6, s30, s6
	s_addc_u32 s7, s31, s7
	s_add_u32 s10, s6, 0x80000
	v_readfirstlane_b32 s3, v144
	s_addc_u32 s11, s7, 0
	s_lshr_b32 s18, s3, 6
	s_lshl_b32 s1, s18, 10
	s_add_i32 s34, s1, 0
	s_add_i32 m0, s34, 0x10000
	v_lshl_or_b32 v154, v3, 12, v1
	global_load_lds_dwordx4 v150, s[4:5]
	s_add_i32 m0, s34, 0x12000
	v_lshl_or_b32 v148, v4, 12, v1
	global_load_lds_dwordx4 v154, s[4:5]
	s_add_i32 m0, s34, 0x14000
	s_add_i32 s35, s34, 0x2000
	global_load_lds_dwordx4 v150, s[8:9]
	s_add_i32 m0, s34, 0x16000
	v_lshl_or_b32 v152, v3, 12, v1
	global_load_lds_dwordx4 v154, s[8:9]
	s_mov_b32 m0, s34
	s_add_i32 s36, s34, 0x4000
	global_load_lds_dwordx4 v148, s[6:7]
	s_mov_b32 m0, s35
	s_add_i32 s37, s34, 0x6000
	global_load_lds_dwordx4 v152, s[6:7]
	s_mov_b32 m0, s36
	v_mov_b32_e32 v151, 0
	global_load_lds_dwordx4 v148, s[10:11]
	s_mov_b32 m0, s37
	s_lshr_b32 s19, s3, 8
	global_load_lds_dwordx4 v152, s[10:11]
	v_mov_b32_e32 v155, v151
	v_mov_b32_e32 v149, v151
	v_mov_b32_e32 v153, v151
	s_cmp_eq_u32 s19, 1
	s_mov_b32 s38, 0
	v_lshl_add_u64 v[0:1], s[4:5], 0, v[150:151]
	v_lshl_add_u64 v[2:3], s[4:5], 0, v[154:155]
	v_lshl_add_u64 v[4:5], s[6:7], 0, v[148:149]
	s_cselect_b64 s[8:9], -1, 0
	s_cmp_lg_u32 s19, 1
	v_lshl_add_u64 v[6:7], s[6:7], 0, v[152:153]
	s_cbranch_scc1 .LBB0_525
	s_barrier
